# attention key-pair loop edge: scalar trip counter (s_add/s_cmp/s_cbranch_scc1) replaces the VALU carry counter and vcc mask; dead K-pointer increment removed
# speedup vs baseline: 1.0138x; 1.0020x over previous
; __device__ __forceinline__ float dot2bf(unsigned a, unsigned b, float c) { return __builtin_amdgcn_fdot2_f32_bf16(__builtin_bit_cast(bf2_t, a), __builtin_bit_cast(bf2_t, b), c, false); }
; __device__ __forceinline__ void attn_item(CPar p, int l, int item, float* wl) {
;     ...
;         const int nk = jt + 1 < 32 ? jt + 1 : 32, npair = (nk + 1) >> 1;
;         for (int m = 0; m < npair; ++m) { const int j0 = jt - 2 * m, j1 = j0 - 1;
;             float z0 = 0.f, z1 = 0.f;
; #pragma unroll
;             for (int d8 = 0; d8 < 8; ++d8) { const u32x4 k0 = *(const u32x4*)(Kt + (2 * m) * 32 + d8 * 4), k1 = *(const u32x4*)(Kt + (2 * m + 1) * 32 + d8 * 4);
; #pragma unroll
;                 for (int c = 0; c < 4; ++c) { z0 = dot2bf(q[d8 * 4 + c], k0[c], z0); z1 = dot2bf(q[d8 * 4 + c], k1[c], z1); } }
.LBB0_770:
	s_min_i32 s6, s1, 31
	s_add_i32 s6, s6, 2
	s_lshr_b32 s6, s6, 1
	s_max_u32 s6, s6, 1
	s_sub_i32 s6, 0, s6
	v_mov_b32_e32 v1, s6
	s_mov_b32 s9, s6
	v_mbcnt_lo_u32_b32 v250, -1, 0
	v_mbcnt_hi_u32_b32 v250, -1, v250
	v_and_b32_e32 v251, 15, v250
	v_lshrrev_b32_e32 v252, 4, v250
	v_lshlrev_b32_e32 v253, 7, v251
	v_lshl_add_u32 v253, v252, 4, v253
	v_add_u32_e32 v253, s52, v253
	v_mul_u32_u24_e32 v251, 0x90, v251
	v_lshl_add_u32 v251, v252, 4, v251
	v_add_u32_e32 v251, s52, v251
	v_add_u32_e32 v251, 0x2000, v251
	ds_read_b128 v[192:195], v253
	ds_read_b128 v[196:199], v253 offset:64
	s_waitcnt lgkmcnt(0)
	v_mfma_f32_16x16x32_bf16 v[216:219], v[192:195], v[80:83], 0
	v_mfma_f32_16x16x32_bf16 v[220:223], v[192:195], v[88:91], 0
	v_mfma_f32_16x16x32_bf16 v[216:219], v[196:199], v[84:87], v[216:219]
	v_mfma_f32_16x16x32_bf16 v[220:223], v[196:199], v[92:95], v[220:223]
	s_nop 7
	s_nop 1
	ds_write_b128 v251, v[216:219]
	ds_write_b128 v251, v[220:223] offset:2304
	s_waitcnt lgkmcnt(0)
	v_mfma_f32_16x16x32_bf16 v[216:219], v[192:195], v[96:99], 0
	v_mfma_f32_16x16x32_bf16 v[220:223], v[192:195], v[104:107], 0
	v_mfma_f32_16x16x32_bf16 v[216:219], v[196:199], v[100:103], v[216:219]
	v_mfma_f32_16x16x32_bf16 v[220:223], v[196:199], v[108:111], v[220:223]
	s_nop 7
	s_nop 1
	ds_write_b128 v251, v[216:219] offset:4608
	ds_write_b128 v251, v[220:223] offset:6912
	s_waitcnt lgkmcnt(0)
	ds_read_b128 v[192:195], v253 offset:2048
	ds_read_b128 v[196:199], v253 offset:2112
	s_waitcnt lgkmcnt(0)
	v_mfma_f32_16x16x32_bf16 v[216:219], v[192:195], v[80:83], 0
	v_mfma_f32_16x16x32_bf16 v[220:223], v[192:195], v[88:91], 0
	v_mfma_f32_16x16x32_bf16 v[216:219], v[196:199], v[84:87], v[216:219]
	v_mfma_f32_16x16x32_bf16 v[220:223], v[196:199], v[92:95], v[220:223]
	s_nop 7
	s_nop 1
	ds_write_b128 v251, v[216:219] offset:64
	ds_write_b128 v251, v[220:223] offset:2368
	s_waitcnt lgkmcnt(0)
	v_mfma_f32_16x16x32_bf16 v[216:219], v[192:195], v[96:99], 0
	v_mfma_f32_16x16x32_bf16 v[220:223], v[192:195], v[104:107], 0
	v_mfma_f32_16x16x32_bf16 v[216:219], v[196:199], v[100:103], v[216:219]
	v_mfma_f32_16x16x32_bf16 v[220:223], v[196:199], v[108:111], v[220:223]
	s_nop 7
	s_nop 1
	ds_write_b128 v251, v[216:219] offset:4672
	ds_write_b128 v251, v[220:223] offset:6976
	s_waitcnt lgkmcnt(0)
	s_waitcnt lgkmcnt(0)
	v_mul_u32_u24_e32 v250, 0x90, v250
	v_add_u32_e32 v250, s52, v250
	v_add_u32_e32 v250, 0x2000, v250
	v_mov_b32_e32 v251, v250
; __device__ __forceinline__ unsigned pk2(float lo, float hi) { unsigned r; asm volatile("v_cvt_pk_bf16_f32 %0, %1, %2" : "=v"(r) : "v"(lo), "v"(hi)); return r; }
; __device__ __forceinline__ float dot2bf(unsigned a, unsigned b, float c) { return __builtin_amdgcn_fdot2_f32_bf16(__builtin_bit_cast(bf2_t, a), __builtin_bit_cast(bf2_t, b), c, false); }
; __device__ __forceinline__ void attn_item(CPar p, int l, int item, float* wl) {
;     ...
;         for (int m = 0; m < npair; ++m) { const int j0 = jt - 2 * m, j1 = j0 - 1;
;             float z0 = 0.f, z1 = 0.f;
; #pragma unroll
;             for (int d8 = 0; d8 < 8; ++d8) { const u32x4 k0 = *(const u32x4*)(Kt + (2 * m) * 32 + d8 * 4), k1 = *(const u32x4*)(Kt + (2 * m + 1) * 32 + d8 * 4);
; #pragma unroll
;                 for (int c = 0; c < 4; ++c) { z0 = dot2bf(q[d8 * 4 + c], k0[c], z0); z1 = dot2bf(q[d8 * 4 + c], k1[c], z1); } }
;             const bool v0 = active && (j0 < nh + i), v1 = active && (j1 >= 0) && (j1 < nh + i);
;             const float e0 = __expf(-z0), ls0 = -__logf(1.f + e0);
;             const float w0 = v0 ? __expf(ls0 + run) : 0.f; run += v0 ? (ls0 - z0) : 0.f;
;             const float e1 = __expf(-z1), ls1 = -__logf(1.f + e1);
;             const float w1 = v1 ? __expf(ls1 + run) : 0.f; run += v1 ? (ls1 - z1) : 0.f;
;             const unsigned wp = pk2(w0, w1);
; #pragma unroll
;             for (int d4 = 0; d4 < 16; ++d4) { const u32x4 vv = *(const u32x4*)(Vp + m * 64 + d4 * 4);
; #pragma unroll
;                 for (int c = 0; c < 4; ++c) o[d4 * 4 + c] = dot2bf(wp, vv[c], o[d4 * 4 + c]); } }
;         __builtin_amdgcn_wave_barrier(); asm volatile("s_waitcnt lgkmcnt(0)" ::: "memory");
;         const int fin = (!active) || (run < -50.f);
;         if (__all(fin)) break;
.LBB0_771:
	ds_read_b64 v[252:253], v250
	v_add_u32_e32 v250, 8, v250
	v_cmp_lt_i32_e32 vcc, s1, v184
	s_and_b64 vcc, s[40:41], vcc
	s_cmp_gt_i32 s1, 0
	s_cselect_b64 s[6:7], -1, 0
	s_and_b64 s[6:7], s[40:41], s[6:7]
	v_cmp_le_i32_e64 s[44:45], s1, v184
	s_add_i32 s1, s1, -2
	s_waitcnt lgkmcnt(0)
	v_mul_f32_e32 v212, 0xbfb8aa3b, v252
	v_mul_f32_e32 v213, 0xbfb8aa3b, v253
	v_exp_f32_e32 v212, v212
	v_exp_f32_e32 v213, v213
	s_and_b64 s[44:45], s[6:7], s[44:45]
	v_add_f32_e32 v212, 1.0, v212
	v_add_f32_e32 v213, 1.0, v213
	v_log_f32_e32 v212, v212
	v_log_f32_e32 v213, v213
	v_mul_f32_e32 v3, 0x3f317217, v212
	v_mul_f32_e32 v79, 0x3f317217, v213
	v_fma_f32 v3, v212, s90, -v3
	v_fma_f32 v79, v213, s90, -v79
	v_fmac_f32_e32 v3, 0x3377d1cf, v212
	v_fmac_f32_e32 v79, 0x3377d1cf, v213
	v_fmac_f32_e32 v3, 0x3f317217, v212
	v_fmac_f32_e32 v79, 0x3f317217, v213
	v_cmp_lt_f32_e64 s[46:47], |v212|, s23
	v_cmp_lt_f32_e64 s[48:49], |v213|, s23
	s_nop 0
	v_cndmask_b32_e64 v212, v212, v3, s[46:47]
	v_cndmask_b32_e64 v213, v213, v79, s[48:49]
	v_sub_f32_e32 v3, v224, v212
	v_sub_f32_e64 v79, -v212, v252
	v_mul_f32_e32 v3, 0x3fb8aa3b, v3
	v_cndmask_b32_e32 v79, 0, v79, vcc
	v_exp_f32_e32 v3, v3
	v_add_f32_e32 v79, v224, v79
	v_sub_f32_e32 v212, v79, v213
	v_sub_f32_e64 v213, -v213, v253
	v_mul_f32_e32 v212, 0x3fb8aa3b, v212
	v_cndmask_b32_e32 v3, 0, v3, vcc
	v_exp_f32_e32 v212, v212
	v_cndmask_b32_e64 v213, 0, v213, s[44:45]
	v_add_f32_e32 v224, v79, v213
	v_cndmask_b32_e64 v212, 0, v212, s[44:45]
	v_cvt_pk_bf16_f32 v212, v3, v212
	ds_write_b32 v251, v212
	v_add_u32_e32 v251, 4, v251
	s_add_i32 s9, s9, 1
	s_cmp_lg_u32 s9, 0
	s_cbranch_scc1 .LBB0_771
	s_mov_b32 s1, 0xc2480000
	v_cmp_gt_f32_e32 vcc, s1, v224
	s_or_b64 s[6:7], s[42:43], vcc
	s_waitcnt lgkmcnt(0)
	v_mbcnt_lo_u32_b32 v250, -1, 0
	v_mbcnt_hi_u32_b32 v250, -1, v250
	v_and_b32_e32 v251, 15, v250
	v_lshrrev_b32_e32 v252, 4, v250
	v_lshlrev_b32_e32 v253, 2, v251
	v_lshl_add_u32 v253, v252, 10, v253
	v_add_u32_e32 v253, s52, v253
	v_add_u32_e32 v253, 0x1000, v253
	v_mul_u32_u24_e32 v251, 0x90, v251
	v_lshl_add_u32 v251, v252, 4, v251
	v_add_u32_e32 v251, s52, v251
	v_add_u32_e32 v251, 0x2000, v251
	ds_read_b128 v[216:219], v251
	ds_read_b128 v[220:223], v251 offset:2304
	ds_read_b32 v192, v253
	ds_read_b32 v193, v253 offset:256
	ds_read_b32 v194, v253 offset:512
	ds_read_b32 v195, v253 offset:768
	ds_read_b32 v196, v253 offset:64
	ds_read_b32 v197, v253 offset:320
	ds_read_b32 v198, v253 offset:576
	ds_read_b32 v199, v253 offset:832
	s_waitcnt lgkmcnt(0)
	v_mfma_f32_16x16x32_bf16 v[124:127], v[192:195], v[216:219], v[124:127]
	v_mfma_f32_16x16x32_bf16 v[140:143], v[192:195], v[220:223], v[140:143]
	v_mfma_f32_16x16x32_bf16 v[128:131], v[196:199], v[216:219], v[128:131]
	v_mfma_f32_16x16x32_bf16 v[144:147], v[196:199], v[220:223], v[144:147]
	s_nop 3
	ds_read_b32 v192, v253 offset:128
	ds_read_b32 v193, v253 offset:384
	ds_read_b32 v194, v253 offset:640
	ds_read_b32 v195, v253 offset:896
	ds_read_b32 v196, v253 offset:192
	ds_read_b32 v197, v253 offset:448
	ds_read_b32 v198, v253 offset:704
	ds_read_b32 v199, v253 offset:960
	s_waitcnt lgkmcnt(0)
	v_mfma_f32_16x16x32_bf16 v[132:135], v[192:195], v[216:219], v[132:135]
	v_mfma_f32_16x16x32_bf16 v[148:151], v[192:195], v[220:223], v[148:151]
	v_mfma_f32_16x16x32_bf16 v[136:139], v[196:199], v[216:219], v[136:139]
	v_mfma_f32_16x16x32_bf16 v[152:155], v[196:199], v[220:223], v[152:155]
	s_nop 3
	ds_read_b128 v[216:219], v251 offset:4608
	ds_read_b128 v[220:223], v251 offset:6912
	ds_read_b32 v192, v253
	ds_read_b32 v193, v253 offset:256
	ds_read_b32 v194, v253 offset:512
	ds_read_b32 v195, v253 offset:768
	ds_read_b32 v196, v253 offset:64
	ds_read_b32 v197, v253 offset:320
	ds_read_b32 v198, v253 offset:576
	ds_read_b32 v199, v253 offset:832
	s_waitcnt lgkmcnt(0)
	v_mfma_f32_16x16x32_bf16 v[176:179], v[192:195], v[216:219], v[176:179]
	v_mfma_f32_16x16x32_bf16 v[234:237], v[192:195], v[220:223], v[234:237]
	v_mfma_f32_16x16x32_bf16 v[180:183], v[196:199], v[216:219], v[180:183]
	v_mfma_f32_16x16x32_bf16 v[238:241], v[196:199], v[220:223], v[238:241]
	s_nop 3
	ds_read_b32 v192, v253 offset:128
	ds_read_b32 v193, v253 offset:384
	ds_read_b32 v194, v253 offset:640
	ds_read_b32 v195, v253 offset:896
	ds_read_b32 v196, v253 offset:192
	ds_read_b32 v197, v253 offset:448
	ds_read_b32 v198, v253 offset:704
	ds_read_b32 v199, v253 offset:960
	s_waitcnt lgkmcnt(0)
	v_mfma_f32_16x16x32_bf16 v[226:229], v[192:195], v[216:219], v[226:229]
	v_mfma_f32_16x16x32_bf16 v[242:245], v[192:195], v[220:223], v[242:245]
	v_mfma_f32_16x16x32_bf16 v[230:233], v[196:199], v[216:219], v[230:233]
	v_mfma_f32_16x16x32_bf16 v[246:249], v[196:199], v[220:223], v[246:249]
	s_nop 3
	v_cndmask_b32_e64 v1, 0, 1, s[6:7]
	v_cmp_ne_u32_e32 vcc, 0, v1
	s_cmp_eq_u64 vcc, exec
	s_cselect_b64 s[28:29], -1, 0
	s_and_b64 vcc, exec, s[28:29]
	s_cbranch_vccz .LBB0_774
	s_branch .LBB0_775
